# combo13
# speedup vs baseline: 1.0210x; 1.0052x over previous
.LBB0_233:
	s_andn2_b64 vcc, exec, s[4:5]
	s_cbranch_vccnz .LBB0_237
	v_readlane_b32 s4, v254, 17
	v_readlane_b32 s5, v254, 18
	s_andn2_b64 vcc, exec, s[4:5]
	s_cbranch_vccnz .LBB0_236
	v_readlane_b32 s4, v254, 20
	v_readlane_b32 s98, v254, 34
	s_mov_b32 s20, s4
	s_mul_i32 s98, s98, 12
	s_add_i32 s20, s20, s98
	s_cmp_gt_i32 s20, 98
	s_cselect_b32 s98, 99, 0
	s_sub_i32 s20, s20, s98
	v_readlane_b32 s4, v254, 23
	s_mov_b64 s[6:7], -1
	s_mov_b32 s18, s4
	s_branch .LBB0_237

.LBB0_245:
	s_andn2_b64 vcc, exec, s[4:5]
	s_cbranch_vccnz .LBB0_249
	s_cmpk_gt_i32 s77, 0x62f
	s_mov_b64 s[16:17], 0
	s_cbranch_scc1 .LBB0_248
	s_mul_hi_i32 s4, s77, 0xa57eb503
	s_add_i32 s4, s4, s77
	s_lshr_b32 s5, s4, 31
	s_ashr_i32 s4, s4, 9
	s_add_i32 s4, s4, s5
	s_mul_i32 s5, s4, 0x318
	s_sub_i32 s5, s77, s5
	s_lshl_b32 s4, s4, 3
	v_readlane_b32 s7, v254, 22
	s_ashr_i32 s6, s5, 3
	s_add_i32 s4, s4, s7
	s_and_b32 s5, s5, 7
	v_readlane_b32 s98, v254, 34
	s_or_b32 s7, s4, s5
	s_mul_i32 s98, s98, 12
	s_add_i32 s6, s6, s98
	s_cmp_gt_i32 s6, 98
	s_cselect_b32 s98, 99, 0
	s_sub_i32 s6, s6, s98
	s_mov_b64 s[16:17], -1
